# GEMM K-loops: LDS read address add hoisted above the second barrier (one fewer slot between barrier and fragment reads)
# speedup vs baseline: 1.0076x; 1.0007x over previous
; template <bool DEEP, class Epi>
; __device__ __forceinline__ void gemm_phase(const bf16_t* __restrict__ A, int lda, const bf16_t* __restrict__ Wt,
;                                            int K, int ntn, bool lat_only, const Epi& epi, char* smem) {
;     ...
;     for (int kt = 0; kt < nk; ++kt) {
;       __syncthreads();
;       GEMM_STORE(ra0, ra1, ra2, ra3, rb0, rb1, rb2, rb3, 0)
;       __syncthreads();
;       {
;         bf16x8 af0[4], bf0[4], af1[4], bf1[4];
;         __builtin_amdgcn_s_setprio(1);
; #pragma unroll
;         for (int i = 0; i < 4; ++i) af0[i] = *(const bf16x8*)(sA + (wm * 64 + i * 16 + l15) * LSTR + quad * 8);
; #pragma unroll
;         for (int j = 0; j < 4; ++j) bf0[j] = *(const bf16x8*)(sB + (wn * 64 + j * 16 + l15) * LSTR + quad * 8);
; #pragma unroll
;         for (int i = 0; i < 4; ++i) af1[i] = *(const bf16x8*)(sA + (wm * 64 + i * 16 + l15) * LSTR + 32 + quad * 8);
; #pragma unroll
;         for (int j = 0; j < 4; ++j) bf1[j] = *(const bf16x8*)(sB + (wn * 64 + j * 16 + l15) * LSTR + 32 + quad * 8);
;         __builtin_amdgcn_sched_barrier(0);
;         if (kt + 1 < nk) GEMM_LOAD(ra0, ra1, ra2, ra3, rb0, rb1, rb2, rb3, (kt + 1) * 64)
.LBB0_140:
	s_barrier
	s_waitcnt vmcnt(7)
	ds_write_b128 v165, v[64:67]
	s_waitcnt vmcnt(6)
	ds_write_b128 v165, v[68:71] offset:5120
	s_waitcnt vmcnt(5)
	ds_write_b128 v165, v[72:75] offset:10240
	s_waitcnt vmcnt(4)
	ds_write_b128 v165, v[76:79] offset:15360
	s_waitcnt vmcnt(3)
	ds_write_b128 v165, v[80:83] offset:20480
	s_waitcnt vmcnt(2)
	ds_write_b128 v165, v[84:87] offset:25600
	s_waitcnt vmcnt(1)
	ds_write_b128 v165, v[88:91] offset:30720
	s_waitcnt vmcnt(0)
	ds_write_b128 v165, v[92:95] offset:35840
	v_add_u32_e32 v96, v173, v175
	s_waitcnt lgkmcnt(0)
	s_barrier
	s_setprio 1
	ds_read_b128 v[156:159], v96
	ds_read_b128 v[152:155], v96 offset:2560
	ds_read_b128 v[132:135], v96 offset:5120
	ds_read_b128 v[124:127], v96 offset:7680
	ds_read_b128 v[136:139], v181 offset:20480
	ds_read_b128 v[140:143], v181 offset:23040
	ds_read_b128 v[144:147], v181 offset:25600
	ds_read_b128 v[148:151], v181 offset:28160
	ds_read_b128 v[128:131], v183 offset:64
	ds_read_b128 v[120:123], v183 offset:2624
	ds_read_b128 v[100:103], v183 offset:5184
	ds_read_b128 v[96:99], v183 offset:7744
	ds_read_b128 v[104:107], v185 offset:20544
	ds_read_b128 v[108:111], v185 offset:23104
	ds_read_b128 v[112:115], v185 offset:25664
	ds_read_b128 v[116:119], v185 offset:28224
	s_cmpk_eq_i32 s0, 0x780
	s_cbranch_scc1 .LBB0_139
	v_lshl_add_u64 v[72:73], v[238:239], 0, s[0:1]
	v_add_co_u32_e32 v64, vcc, 0x1d00000, v72
	v_lshl_add_u64 v[88:89], v[240:241], 0, s[0:1]
	s_nop 0
	v_addc_co_u32_e32 v65, vcc, 0, v73, vcc
	v_add_co_u32_e32 v68, vcc, 0x1d10000, v72
	s_nop 1
	v_addc_co_u32_e32 v69, vcc, 0, v73, vcc
	v_add_co_u32_e32 v74, vcc, 0x1d20000, v72
	global_load_dwordx4 v[64:67], v[64:65], off offset:128
	s_nop 0
	global_load_dwordx4 v[68:71], v[68:69], off offset:128
	v_addc_co_u32_e32 v75, vcc, 0, v73, vcc
	v_add_co_u32_e32 v76, vcc, 0x1d30000, v72
	s_nop 1
	v_addc_co_u32_e32 v77, vcc, 0, v73, vcc
	v_add_co_u32_e32 v84, vcc, 0x10000, v88
	global_load_dwordx4 v[72:75], v[74:75], off offset:128
	s_nop 0
	global_load_dwordx4 v[76:79], v[76:77], off offset:128
	v_addc_co_u32_e32 v85, vcc, 0, v89, vcc
	v_add_co_u32_e32 v90, vcc, 0x20000, v88
	global_load_dwordx4 v[80:83], v[88:89], off offset:128
	s_nop 0
	global_load_dwordx4 v[84:87], v[84:85], off offset:128
	v_addc_co_u32_e32 v91, vcc, 0, v89, vcc
	v_add_co_u32_e32 v92, vcc, 0x30000, v88
	s_nop 1
	v_addc_co_u32_e32 v93, vcc, 0, v89, vcc
	global_load_dwordx4 v[88:91], v[90:91], off offset:128
	s_nop 0
	global_load_dwordx4 v[92:95], v[92:93], off offset:128
	s_branch .LBB0_139

; template <bool DEEP, class Epi>
; __device__ __forceinline__ void gemm_phase(const bf16_t* __restrict__ A, int lda, const bf16_t* __restrict__ Wt,
;                                            int K, int ntn, bool lat_only, const Epi& epi, char* smem) {
;     ...
;     for (int kt = 0; kt < nk; ++kt) {
;       __syncthreads();
;       GEMM_STORE(ra0, ra1, ra2, ra3, rb0, rb1, rb2, rb3, 0)
;       __syncthreads();
;       {
;         bf16x8 af0[4], bf0[4], af1[4], bf1[4];
;         __builtin_amdgcn_s_setprio(1);
; #pragma unroll
;         for (int i = 0; i < 4; ++i) af0[i] = *(const bf16x8*)(sA + (wm * 64 + i * 16 + l15) * LSTR + quad * 8);
; #pragma unroll
;         for (int j = 0; j < 4; ++j) bf0[j] = *(const bf16x8*)(sB + (wn * 64 + j * 16 + l15) * LSTR + quad * 8);
; #pragma unroll
;         for (int i = 0; i < 4; ++i) af1[i] = *(const bf16x8*)(sA + (wm * 64 + i * 16 + l15) * LSTR + 32 + quad * 8);
; #pragma unroll
;         for (int j = 0; j < 4; ++j) bf1[j] = *(const bf16x8*)(sB + (wn * 64 + j * 16 + l15) * LSTR + 32 + quad * 8);
;         __builtin_amdgcn_sched_barrier(0);
;         if (kt + 1 < nk) GEMM_LOAD(ra0, ra1, ra2, ra3, rb0, rb1, rb2, rb3, (kt + 1) * 64)
.LBB0_438:
	s_waitcnt vmcnt(63) expcnt(7) lgkmcnt(15)
	s_barrier
	s_waitcnt vmcnt(0)
	ds_write_b128 v161, v[64:67]
	ds_write_b128 v161, v[68:71] offset:5120
	ds_write_b128 v161, v[80:83] offset:10240
	ds_write_b128 v161, v[88:91] offset:15360
	ds_write_b128 v161, v[72:75] offset:20480
	ds_write_b128 v161, v[76:79] offset:25600
	ds_write_b128 v161, v[84:87] offset:30720
	ds_write_b128 v161, v[92:95] offset:35840
	v_add_u32_e32 v96, v175, v178
	s_waitcnt lgkmcnt(0)
	s_barrier
	s_setprio 1
	ds_read_b128 v[156:159], v96
	ds_read_b128 v[152:155], v96 offset:2560
	ds_read_b128 v[132:135], v96 offset:5120
	ds_read_b128 v[124:127], v96 offset:7680
	ds_read_b128 v[136:139], v180 offset:20480
	ds_read_b128 v[140:143], v180 offset:23040
	ds_read_b128 v[144:147], v180 offset:25600
	ds_read_b128 v[148:151], v180 offset:28160
	ds_read_b128 v[128:131], v182 offset:64
	ds_read_b128 v[120:123], v182 offset:2624
	ds_read_b128 v[100:103], v182 offset:5184
	ds_read_b128 v[96:99], v182 offset:7744
	ds_read_b128 v[104:107], v183 offset:20544
	ds_read_b128 v[108:111], v183 offset:23104
	ds_read_b128 v[112:115], v183 offset:25664
	ds_read_b128 v[116:119], v183 offset:28224
	s_cmp_gt_u32 s1, 14
	s_cbranch_scc1 .LBB0_437
	v_lshl_add_u64 v[72:73], v[170:171], 0, s[12:13]
	v_add_co_u32_e32 v64, vcc, 0x1d00000, v72
	v_lshl_add_u64 v[84:85], v[172:173], 0, s[12:13]
	s_nop 0
	v_addc_co_u32_e32 v65, vcc, 0, v73, vcc
	v_add_co_u32_e32 v68, vcc, 0x1d10000, v72
	s_nop 1
	v_addc_co_u32_e32 v69, vcc, 0, v73, vcc
	v_add_co_u32_e32 v74, vcc, 0x1d20000, v72
	global_load_dwordx4 v[64:67], v[64:65], off offset:128
	s_nop 0
	global_load_dwordx4 v[68:71], v[68:69], off offset:128
	v_addc_co_u32_e32 v75, vcc, 0, v73, vcc
	v_add_co_u32_e32 v72, vcc, 0x1d30000, v72
	s_nop 1
	v_addc_co_u32_e32 v73, vcc, 0, v73, vcc
	global_load_dwordx4 v[80:83], v[74:75], off offset:128
	global_load_dwordx4 v[88:91], v[72:73], off offset:128
	v_add_co_u32_e32 v72, vcc, 0x680000, v84
	s_nop 1
	v_addc_co_u32_e32 v73, vcc, 0, v85, vcc
	v_add_co_u32_e32 v76, vcc, 0x690000, v84
	s_nop 1
	v_addc_co_u32_e32 v77, vcc, 0, v85, vcc
	v_add_co_u32_e32 v86, vcc, 0x6a0000, v84
	global_load_dwordx4 v[72:75], v[72:73], off offset:128
	s_nop 0
	global_load_dwordx4 v[76:79], v[76:77], off offset:128
	v_addc_co_u32_e32 v87, vcc, 0, v85, vcc
	v_add_co_u32_e32 v92, vcc, 0x6b0000, v84
	s_nop 1
	v_addc_co_u32_e32 v93, vcc, 0, v85, vcc
	global_load_dwordx4 v[84:87], v[86:87], off offset:128
	s_nop 0
	global_load_dwordx4 v[92:95], v[92:93], off offset:128
	s_branch .LBB0_437

; template <bool DEEP, class Epi>
; __device__ __forceinline__ void gemm_phase(const bf16_t* __restrict__ A, int lda, const bf16_t* __restrict__ Wt,
;                                            int K, int ntn, bool lat_only, const Epi& epi, char* smem) {
;     ...
;     for (int kt = 0; kt < nk; ++kt) {
;       __syncthreads();
;       GEMM_STORE(ra0, ra1, ra2, ra3, rb0, rb1, rb2, rb3, 0)
;       __syncthreads();
;       {
;         bf16x8 af0[4], bf0[4], af1[4], bf1[4];
;         __builtin_amdgcn_s_setprio(1);
; #pragma unroll
;         for (int i = 0; i < 4; ++i) af0[i] = *(const bf16x8*)(sA + (wm * 64 + i * 16 + l15) * LSTR + quad * 8);
; #pragma unroll
;         for (int j = 0; j < 4; ++j) bf0[j] = *(const bf16x8*)(sB + (wn * 64 + j * 16 + l15) * LSTR + quad * 8);
; #pragma unroll
;         for (int i = 0; i < 4; ++i) af1[i] = *(const bf16x8*)(sA + (wm * 64 + i * 16 + l15) * LSTR + 32 + quad * 8);
; #pragma unroll
;         for (int j = 0; j < 4; ++j) bf1[j] = *(const bf16x8*)(sB + (wn * 64 + j * 16 + l15) * LSTR + 32 + quad * 8);
;         __builtin_amdgcn_sched_barrier(0);
;         if (kt + 1 < nk) GEMM_LOAD(ra0, ra1, ra2, ra3, rb0, rb1, rb2, rb3, (kt + 1) * 64)
.LBB0_576:
	s_waitcnt vmcnt(63) expcnt(7) lgkmcnt(15)
	s_barrier
	s_waitcnt vmcnt(7)
	ds_write_b128 v176, v[56:59]
	s_waitcnt vmcnt(6)
	ds_write_b128 v176, v[60:63] offset:5120
	s_waitcnt vmcnt(5)
	ds_write_b128 v176, v[68:71] offset:10240
	s_waitcnt vmcnt(4)
	ds_write_b128 v176, v[76:79] offset:15360
	s_waitcnt vmcnt(3)
	ds_write_b128 v176, v[80:83] offset:20480
	s_waitcnt vmcnt(2)
	ds_write_b128 v176, v[84:87] offset:25600
	s_waitcnt vmcnt(1)
	ds_write_b128 v176, v[88:91] offset:30720
	s_waitcnt vmcnt(0)
	ds_write_b128 v176, v[92:95] offset:35840
	v_add_u32_e32 v96, v180, v182
	s_waitcnt lgkmcnt(0)
	s_barrier
	s_setprio 1
	ds_read_b128 v[156:159], v96
	ds_read_b128 v[152:155], v96 offset:2560
	ds_read_b128 v[132:135], v96 offset:5120
	ds_read_b128 v[124:127], v96 offset:7680
	ds_read_b128 v[136:139], v183 offset:20480
	ds_read_b128 v[140:143], v183 offset:23040
	ds_read_b128 v[144:147], v183 offset:25600
	ds_read_b128 v[148:151], v183 offset:28160
	ds_read_b128 v[128:131], v184 offset:64
	ds_read_b128 v[120:123], v184 offset:2624
	ds_read_b128 v[100:103], v184 offset:5184
	ds_read_b128 v[96:99], v184 offset:7744
	ds_read_b128 v[104:107], v185 offset:20544
	ds_read_b128 v[108:111], v185 offset:23104
	ds_read_b128 v[112:115], v185 offset:25664
	ds_read_b128 v[116:119], v185 offset:28224
	s_cmpk_eq_i32 s8, 0x780
	s_cbranch_scc1 .LBB0_575
	v_lshl_add_u64 v[68:69], v[172:173], 0, s[8:9]
	v_add_co_u32_e32 v56, vcc, 0x1d00000, v68
	v_lshl_add_u64 v[88:89], v[174:175], 0, s[8:9]
	s_nop 0
	v_addc_co_u32_e32 v57, vcc, 0, v69, vcc
	v_add_co_u32_e32 v60, vcc, 0x1d10000, v68
	s_nop 1
	v_addc_co_u32_e32 v61, vcc, 0, v69, vcc
	v_add_co_u32_e32 v70, vcc, 0x1d20000, v68
	global_load_dwordx4 v[56:59], v[56:57], off offset:128
	s_nop 0
	global_load_dwordx4 v[60:63], v[60:61], off offset:128
	v_addc_co_u32_e32 v71, vcc, 0, v69, vcc
	v_add_co_u32_e32 v76, vcc, 0x1d30000, v68
	s_nop 1
	v_addc_co_u32_e32 v77, vcc, 0, v69, vcc
	v_add_co_u32_e32 v80, vcc, 0x880000, v88
	global_load_dwordx4 v[68:71], v[70:71], off offset:128
	s_nop 0
	global_load_dwordx4 v[76:79], v[76:77], off offset:128
	v_addc_co_u32_e32 v81, vcc, 0, v89, vcc
	v_add_co_u32_e32 v84, vcc, 0x890000, v88
	s_nop 1
	v_addc_co_u32_e32 v85, vcc, 0, v89, vcc
	v_add_co_u32_e32 v90, vcc, 0x8a0000, v88
	global_load_dwordx4 v[80:83], v[80:81], off offset:128
	s_nop 0
	global_load_dwordx4 v[84:87], v[84:85], off offset:128
	v_addc_co_u32_e32 v91, vcc, 0, v89, vcc
	v_add_co_u32_e32 v92, vcc, 0x8b0000, v88
	s_nop 1
	v_addc_co_u32_e32 v93, vcc, 0, v89, vcc
	global_load_dwordx4 v[88:91], v[90:91], off offset:128
	s_nop 0
	global_load_dwordx4 v[92:95], v[92:93], off offset:128
	s_branch .LBB0_575

; template <bool DEEP, class Epi>
; __device__ __forceinline__ void gemm_phase(const bf16_t* __restrict__ A, int lda, const bf16_t* __restrict__ Wt,
;                                            int K, int ntn, bool lat_only, const Epi& epi, char* smem) {
;     ...
;     for (int kt = 0; kt < nk; ++kt) {
;       __syncthreads();
;       GEMM_STORE(ra0, ra1, ra2, ra3, rb0, rb1, rb2, rb3, 0)
;       __syncthreads();
;       {
;         bf16x8 af0[4], bf0[4], af1[4], bf1[4];
;         __builtin_amdgcn_s_setprio(1);
; #pragma unroll
;         for (int i = 0; i < 4; ++i) af0[i] = *(const bf16x8*)(sA + (wm * 64 + i * 16 + l15) * LSTR + quad * 8);
; #pragma unroll
;         for (int j = 0; j < 4; ++j) bf0[j] = *(const bf16x8*)(sB + (wn * 64 + j * 16 + l15) * LSTR + quad * 8);
; #pragma unroll
;         for (int i = 0; i < 4; ++i) af1[i] = *(const bf16x8*)(sA + (wm * 64 + i * 16 + l15) * LSTR + 32 + quad * 8);
; #pragma unroll
;         for (int j = 0; j < 4; ++j) bf1[j] = *(const bf16x8*)(sB + (wn * 64 + j * 16 + l15) * LSTR + 32 + quad * 8);
;         __builtin_amdgcn_sched_barrier(0);
;         if (kt + 1 < nk) GEMM_LOAD(ra0, ra1, ra2, ra3, rb0, rb1, rb2, rb3, (kt + 1) * 64)
.LBB0_635:
	s_waitcnt vmcnt(63) expcnt(7) lgkmcnt(15)
	s_barrier
	s_waitcnt vmcnt(0)
	ds_write_b128 v161, v[64:67]
	ds_write_b128 v161, v[68:71] offset:5120
	ds_write_b128 v161, v[80:83] offset:10240
	ds_write_b128 v161, v[88:91] offset:15360
	ds_write_b128 v161, v[72:75] offset:20480
	ds_write_b128 v161, v[76:79] offset:25600
	ds_write_b128 v161, v[84:87] offset:30720
	ds_write_b128 v161, v[92:95] offset:35840
	v_add_u32_e32 v96, v175, v178
	s_waitcnt lgkmcnt(0)
	s_barrier
	s_setprio 1
	ds_read_b128 v[156:159], v96
	ds_read_b128 v[152:155], v96 offset:2560
	ds_read_b128 v[132:135], v96 offset:5120
	ds_read_b128 v[124:127], v96 offset:7680
	ds_read_b128 v[136:139], v182 offset:20480
	ds_read_b128 v[140:143], v182 offset:23040
	ds_read_b128 v[144:147], v182 offset:25600
	ds_read_b128 v[148:151], v182 offset:28160
	ds_read_b128 v[128:131], v183 offset:64
	ds_read_b128 v[120:123], v183 offset:2624
	ds_read_b128 v[100:103], v183 offset:5184
	ds_read_b128 v[96:99], v183 offset:7744
	ds_read_b128 v[104:107], v184 offset:20544
	ds_read_b128 v[108:111], v184 offset:23104
	ds_read_b128 v[112:115], v184 offset:25664
	ds_read_b128 v[116:119], v184 offset:28224
	s_cmp_gt_u32 s15, 42
	s_cbranch_scc1 .LBB0_634
	v_lshl_add_u64 v[72:73], v[170:171], 0, s[0:1]
	v_add_co_u32_e32 v64, vcc, 0x5e00000, v72
	v_lshl_add_u64 v[84:85], v[172:173], 0, s[0:1]
	s_nop 0
	v_addc_co_u32_e32 v65, vcc, 0, v73, vcc
	v_add_co_u32_e32 v68, vcc, 0x5e2c000, v72
	s_nop 1
	v_addc_co_u32_e32 v69, vcc, 0, v73, vcc
	v_add_co_u32_e32 v74, vcc, 0x5e58000, v72
	global_load_dwordx4 v[64:67], v[64:65], off offset:128
	s_nop 0
	global_load_dwordx4 v[68:71], v[68:69], off offset:128
	v_addc_co_u32_e32 v75, vcc, 0, v73, vcc
	v_add_co_u32_e32 v72, vcc, 0x5e84000, v72
	s_nop 1
	v_addc_co_u32_e32 v73, vcc, 0, v73, vcc
	global_load_dwordx4 v[80:83], v[74:75], off offset:128
	global_load_dwordx4 v[88:91], v[72:73], off offset:128
	v_add_co_u32_e32 v72, vcc, 0x1380000, v84
	s_nop 1
	v_addc_co_u32_e32 v73, vcc, 0, v85, vcc
	v_add_co_u32_e32 v76, vcc, 0x13ac000, v84
	s_nop 1
	v_addc_co_u32_e32 v77, vcc, 0, v85, vcc
	v_add_co_u32_e32 v86, vcc, 0x13d8000, v84
	global_load_dwordx4 v[72:75], v[72:73], off offset:128
	s_nop 0
	global_load_dwordx4 v[76:79], v[76:77], off offset:128
	v_addc_co_u32_e32 v87, vcc, 0, v85, vcc
	v_add_co_u32_e32 v92, vcc, 0x1404000, v84
	s_nop 1
	v_addc_co_u32_e32 v93, vcc, 0, v85, vcc
	global_load_dwordx4 v[84:87], v[86:87], off offset:128
	s_nop 0
	global_load_dwordx4 v[92:95], v[92:93], off offset:128
	s_branch .LBB0_634

; template <bool DEEP, class Epi>
; __device__ __forceinline__ void gemm_phase(const bf16_t* __restrict__ A, int lda, const bf16_t* __restrict__ Wt,
;                                            int K, int ntn, bool lat_only, const Epi& epi, char* smem) {
;     ...
;     for (int kt = 0; kt < nk; ++kt) {
;       __syncthreads();
;       GEMM_STORE(ra0, ra1, ra2, ra3, rb0, rb1, rb2, rb3, 0)
;       __syncthreads();
;       {
;         bf16x8 af0[4], bf0[4], af1[4], bf1[4];
;         __builtin_amdgcn_s_setprio(1);
; #pragma unroll
;         for (int i = 0; i < 4; ++i) af0[i] = *(const bf16x8*)(sA + (wm * 64 + i * 16 + l15) * LSTR + quad * 8);
; #pragma unroll
;         for (int j = 0; j < 4; ++j) bf0[j] = *(const bf16x8*)(sB + (wn * 64 + j * 16 + l15) * LSTR + quad * 8);
; #pragma unroll
;         for (int i = 0; i < 4; ++i) af1[i] = *(const bf16x8*)(sA + (wm * 64 + i * 16 + l15) * LSTR + 32 + quad * 8);
; #pragma unroll
;         for (int j = 0; j < 4; ++j) bf1[j] = *(const bf16x8*)(sB + (wn * 64 + j * 16 + l15) * LSTR + 32 + quad * 8);
;         __builtin_amdgcn_sched_barrier(0);
;         if (kt + 1 < nk) GEMM_LOAD(ra0, ra1, ra2, ra3, rb0, rb1, rb2, rb3, (kt + 1) * 64)
.LBB0_848:
	s_waitcnt vmcnt(63) expcnt(7) lgkmcnt(15)
	s_barrier
	s_waitcnt vmcnt(7)
	ds_write_b128 v173, v[64:67]
	s_waitcnt vmcnt(6)
	ds_write_b128 v173, v[68:71] offset:5120
	s_waitcnt vmcnt(5)
	ds_write_b128 v173, v[72:75] offset:10240
	s_waitcnt vmcnt(4)
	ds_write_b128 v173, v[76:79] offset:15360
	s_waitcnt vmcnt(3)
	ds_write_b128 v173, v[80:83] offset:20480
	s_waitcnt vmcnt(2)
	ds_write_b128 v173, v[84:87] offset:25600
	s_waitcnt vmcnt(1)
	ds_write_b128 v173, v[88:91] offset:30720
	s_waitcnt vmcnt(0)
	ds_write_b128 v173, v[92:95] offset:35840
	v_add_u32_e32 v96, v183, v187
	s_waitcnt lgkmcnt(0)
	s_barrier
	s_setprio 1
	ds_read_b128 v[156:159], v96
	ds_read_b128 v[152:155], v96 offset:2560
	ds_read_b128 v[132:135], v96 offset:5120
	ds_read_b128 v[124:127], v96 offset:7680
	ds_read_b128 v[136:139], v189 offset:20480
	ds_read_b128 v[140:143], v189 offset:23040
	ds_read_b128 v[144:147], v189 offset:25600
	ds_read_b128 v[148:151], v189 offset:28160
	ds_read_b128 v[128:131], v191 offset:64
	ds_read_b128 v[120:123], v191 offset:2624
	ds_read_b128 v[100:103], v191 offset:5184
	ds_read_b128 v[96:99], v191 offset:7744
	ds_read_b128 v[104:107], v193 offset:20544
	ds_read_b128 v[108:111], v193 offset:23104
	ds_read_b128 v[112:115], v193 offset:25664
	ds_read_b128 v[116:119], v193 offset:28224
	s_cmpk_eq_i32 s6, 0x780
	s_cbranch_scc1 .LBB0_847
	v_lshl_add_u64 v[72:73], v[204:205], 0, s[6:7]
	v_add_co_u32_e32 v64, vcc, 0x1d00000, v72
	v_lshl_add_u64 v[88:89], v[206:207], 0, s[6:7]
	s_nop 0
	v_addc_co_u32_e32 v65, vcc, 0, v73, vcc
	v_add_co_u32_e32 v68, vcc, 0x1d10000, v72
	s_nop 1
	v_addc_co_u32_e32 v69, vcc, 0, v73, vcc
	v_add_co_u32_e32 v74, vcc, 0x1d20000, v72
	global_load_dwordx4 v[64:67], v[64:65], off offset:128
	s_nop 0
	global_load_dwordx4 v[68:71], v[68:69], off offset:128
	v_addc_co_u32_e32 v75, vcc, 0, v73, vcc
	v_add_co_u32_e32 v76, vcc, 0x1d30000, v72
	s_nop 1
	v_addc_co_u32_e32 v77, vcc, 0, v73, vcc
	v_add_co_u32_e32 v84, vcc, 0x10000, v88
	global_load_dwordx4 v[72:75], v[74:75], off offset:128
	s_nop 0
	global_load_dwordx4 v[76:79], v[76:77], off offset:128
	v_addc_co_u32_e32 v85, vcc, 0, v89, vcc
	v_add_co_u32_e32 v90, vcc, 0x20000, v88
	global_load_dwordx4 v[80:83], v[88:89], off offset:128
	s_nop 0
	global_load_dwordx4 v[84:87], v[84:85], off offset:128
	v_addc_co_u32_e32 v91, vcc, 0, v89, vcc
	v_add_co_u32_e32 v92, vcc, 0x30000, v88
	s_nop 1
	v_addc_co_u32_e32 v93, vcc, 0, v89, vcc
	global_load_dwordx4 v[88:91], v[90:91], off offset:128
	s_nop 0
	global_load_dwordx4 v[92:95], v[92:93], off offset:128
	s_branch .LBB0_847

; template <bool DEEP, class Epi>
; __device__ __forceinline__ void gemm_phase(const bf16_t* __restrict__ A, int lda, const bf16_t* __restrict__ Wt,
;                                            int K, int ntn, bool lat_only, const Epi& epi, char* smem) {
;     ...
;     for (int kt = 0; kt < nk; ++kt) {
;       __syncthreads();
;       GEMM_STORE(ra0, ra1, ra2, ra3, rb0, rb1, rb2, rb3, 0)
;       __syncthreads();
;       {
;         bf16x8 af0[4], bf0[4], af1[4], bf1[4];
;         __builtin_amdgcn_s_setprio(1);
; #pragma unroll
;         for (int i = 0; i < 4; ++i) af0[i] = *(const bf16x8*)(sA + (wm * 64 + i * 16 + l15) * LSTR + quad * 8);
; #pragma unroll
;         for (int j = 0; j < 4; ++j) bf0[j] = *(const bf16x8*)(sB + (wn * 64 + j * 16 + l15) * LSTR + quad * 8);
; #pragma unroll
;         for (int i = 0; i < 4; ++i) af1[i] = *(const bf16x8*)(sA + (wm * 64 + i * 16 + l15) * LSTR + 32 + quad * 8);
; #pragma unroll
;         for (int j = 0; j < 4; ++j) bf1[j] = *(const bf16x8*)(sB + (wn * 64 + j * 16 + l15) * LSTR + 32 + quad * 8);
;         __builtin_amdgcn_sched_barrier(0);
;         if (kt + 1 < nk) GEMM_LOAD(ra0, ra1, ra2, ra3, rb0, rb1, rb2, rb3, (kt + 1) * 64)
.LBB0_1421:
	s_barrier
	s_waitcnt vmcnt(0)
	ds_write_b128 v161, v[64:67]
	ds_write_b128 v161, v[68:71] offset:5120
	ds_write_b128 v161, v[76:79] offset:10240
	ds_write_b128 v161, v[84:87] offset:15360
	ds_write_b128 v161, v[72:75] offset:20480
	ds_write_b128 v161, v[80:83] offset:25600
	ds_write_b128 v161, v[88:91] offset:30720
	ds_write_b128 v161, v[92:95] offset:35840
	v_add_u32_e32 v96, v173, v175
	s_waitcnt lgkmcnt(0)
	s_barrier
	s_setprio 1
	ds_read_b128 v[156:159], v96
	ds_read_b128 v[152:155], v96 offset:2560
	ds_read_b128 v[132:135], v96 offset:5120
	ds_read_b128 v[124:127], v96 offset:7680
	ds_read_b128 v[136:139], v176 offset:20480
	ds_read_b128 v[140:143], v176 offset:23040
	ds_read_b128 v[144:147], v176 offset:25600
	ds_read_b128 v[148:151], v176 offset:28160
	ds_read_b128 v[128:131], v178 offset:64
	ds_read_b128 v[120:123], v178 offset:2624
	ds_read_b128 v[100:103], v178 offset:5184
	ds_read_b128 v[96:99], v178 offset:7744
	ds_read_b128 v[104:107], v179 offset:20544
	ds_read_b128 v[108:111], v179 offset:23104
	ds_read_b128 v[112:115], v179 offset:25664
	ds_read_b128 v[116:119], v179 offset:28224
	s_cmp_gt_u32 s1, 14
	s_cbranch_scc1 .LBB0_1420
	v_lshl_add_u64 v[72:73], v[168:169], 0, s[8:9]
	v_add_co_u32_e32 v64, vcc, 0x1d00000, v72
	v_lshl_add_u64 v[88:89], v[170:171], 0, s[8:9]
	s_nop 0
	v_addc_co_u32_e32 v65, vcc, 0, v73, vcc
	v_add_co_u32_e32 v68, vcc, 0x1d10000, v72
	s_nop 1
	v_addc_co_u32_e32 v69, vcc, 0, v73, vcc
	v_add_co_u32_e32 v74, vcc, 0x1d20000, v72
	global_load_dwordx4 v[64:67], v[64:65], off offset:128
	s_nop 0
	global_load_dwordx4 v[68:71], v[68:69], off offset:128
	v_addc_co_u32_e32 v75, vcc, 0, v73, vcc
	v_add_co_u32_e32 v72, vcc, 0x1d30000, v72
	s_nop 1
	v_addc_co_u32_e32 v73, vcc, 0, v73, vcc
	global_load_dwordx4 v[76:79], v[74:75], off offset:128
	global_load_dwordx4 v[84:87], v[72:73], off offset:128
	v_add_co_u32_e32 v72, vcc, 0x680000, v88
	s_nop 1
	v_addc_co_u32_e32 v73, vcc, 0, v89, vcc
	v_add_co_u32_e32 v80, vcc, 0x690000, v88
	s_nop 1
	v_addc_co_u32_e32 v81, vcc, 0, v89, vcc
	v_add_co_u32_e32 v90, vcc, 0x6a0000, v88
	global_load_dwordx4 v[72:75], v[72:73], off offset:128
	s_nop 0
	global_load_dwordx4 v[80:83], v[80:81], off offset:128
	v_addc_co_u32_e32 v91, vcc, 0, v89, vcc
	v_add_co_u32_e32 v92, vcc, 0x6b0000, v88
	s_nop 1
	v_addc_co_u32_e32 v93, vcc, 0, v89, vcc
	global_load_dwordx4 v[88:91], v[90:91], off offset:128
	s_nop 0
	global_load_dwordx4 v[92:95], v[92:93], off offset:128
	s_branch .LBB0_1420

; template <bool DEEP, class Epi>
; __device__ __forceinline__ void gemm_phase(const bf16_t* __restrict__ A, int lda, const bf16_t* __restrict__ Wt,
;                                            int K, int ntn, bool lat_only, const Epi& epi, char* smem) {
;     ...
;     for (int kt = 0; kt < nk; ++kt) {
;       __syncthreads();
;       GEMM_STORE(ra0, ra1, ra2, ra3, rb0, rb1, rb2, rb3, 0)
;       __syncthreads();
;       {
;         bf16x8 af0[4], bf0[4], af1[4], bf1[4];
;         __builtin_amdgcn_s_setprio(1);
; #pragma unroll
;         for (int i = 0; i < 4; ++i) af0[i] = *(const bf16x8*)(sA + (wm * 64 + i * 16 + l15) * LSTR + quad * 8);
; #pragma unroll
;         for (int j = 0; j < 4; ++j) bf0[j] = *(const bf16x8*)(sB + (wn * 64 + j * 16 + l15) * LSTR + quad * 8);
; #pragma unroll
;         for (int i = 0; i < 4; ++i) af1[i] = *(const bf16x8*)(sA + (wm * 64 + i * 16 + l15) * LSTR + 32 + quad * 8);
; #pragma unroll
;         for (int j = 0; j < 4; ++j) bf1[j] = *(const bf16x8*)(sB + (wn * 64 + j * 16 + l15) * LSTR + 32 + quad * 8);
;         __builtin_amdgcn_sched_barrier(0);
;         if (kt + 1 < nk) GEMM_LOAD(ra0, ra1, ra2, ra3, rb0, rb1, rb2, rb3, (kt + 1) * 64)
.LBB0_1559:
	s_barrier
	s_waitcnt vmcnt(7)
	ds_write_b128 v172, v[56:59]
	s_waitcnt vmcnt(6)
	ds_write_b128 v172, v[60:63] offset:5120
	s_waitcnt vmcnt(5)
	ds_write_b128 v172, v[64:67] offset:10240
	s_waitcnt vmcnt(4)
	ds_write_b128 v172, v[72:75] offset:15360
	s_waitcnt vmcnt(3)
	ds_write_b128 v172, v[80:83] offset:20480
	s_waitcnt vmcnt(2)
	ds_write_b128 v172, v[84:87] offset:25600
	s_waitcnt vmcnt(1)
	ds_write_b128 v172, v[88:91] offset:30720
	s_waitcnt vmcnt(0)
	ds_write_b128 v172, v[92:95] offset:35840
	v_add_u32_e32 v96, v174, v175
	s_waitcnt lgkmcnt(0)
	s_barrier
	s_setprio 1
	ds_read_b128 v[156:159], v96
	ds_read_b128 v[152:155], v96 offset:2560
	ds_read_b128 v[132:135], v96 offset:5120
	ds_read_b128 v[124:127], v96 offset:7680
	ds_read_b128 v[136:139], v176 offset:20480
	ds_read_b128 v[140:143], v176 offset:23040
	ds_read_b128 v[144:147], v176 offset:25600
	ds_read_b128 v[148:151], v176 offset:28160
	ds_read_b128 v[128:131], v177 offset:64
	ds_read_b128 v[120:123], v177 offset:2624
	ds_read_b128 v[100:103], v177 offset:5184
	ds_read_b128 v[96:99], v177 offset:7744
	ds_read_b128 v[104:107], v178 offset:20544
	ds_read_b128 v[108:111], v178 offset:23104
	ds_read_b128 v[112:115], v178 offset:25664
	ds_read_b128 v[116:119], v178 offset:28224
	s_cmpk_eq_i32 s6, 0x780
	s_cbranch_scc1 .LBB0_1558
	v_lshl_add_u64 v[64:65], v[168:169], 0, s[6:7]
	v_add_co_u32_e32 v56, vcc, 0x1d00000, v64
	v_lshl_add_u64 v[88:89], v[170:171], 0, s[6:7]
	s_nop 0
	v_addc_co_u32_e32 v57, vcc, 0, v65, vcc
	v_add_co_u32_e32 v60, vcc, 0x1d10000, v64
	s_nop 1
	v_addc_co_u32_e32 v61, vcc, 0, v65, vcc
	v_add_co_u32_e32 v66, vcc, 0x1d20000, v64
	global_load_dwordx4 v[56:59], v[56:57], off offset:128
	s_nop 0
	global_load_dwordx4 v[60:63], v[60:61], off offset:128
	v_addc_co_u32_e32 v67, vcc, 0, v65, vcc
	v_add_co_u32_e32 v72, vcc, 0x1d30000, v64
	s_nop 1
	v_addc_co_u32_e32 v73, vcc, 0, v65, vcc
	v_add_co_u32_e32 v80, vcc, 0x880000, v88
	global_load_dwordx4 v[64:67], v[66:67], off offset:128
	s_nop 0
	global_load_dwordx4 v[72:75], v[72:73], off offset:128
	v_addc_co_u32_e32 v81, vcc, 0, v89, vcc
	v_add_co_u32_e32 v84, vcc, 0x890000, v88
	s_nop 1
	v_addc_co_u32_e32 v85, vcc, 0, v89, vcc
	v_add_co_u32_e32 v90, vcc, 0x8a0000, v88
	global_load_dwordx4 v[80:83], v[80:81], off offset:128
	s_nop 0
	global_load_dwordx4 v[84:87], v[84:85], off offset:128
	v_addc_co_u32_e32 v91, vcc, 0, v89, vcc
	v_add_co_u32_e32 v92, vcc, 0x8b0000, v88
	s_nop 1
	v_addc_co_u32_e32 v93, vcc, 0, v89, vcc
	global_load_dwordx4 v[88:91], v[90:91], off offset:128
	s_nop 0
	global_load_dwordx4 v[92:95], v[92:93], off offset:128
	s_branch .LBB0_1558

; template <bool DEEP, class Epi>
; __device__ __forceinline__ void gemm_phase(const bf16_t* __restrict__ A, int lda, const bf16_t* __restrict__ Wt,
;                                            int K, int ntn, bool lat_only, const Epi& epi, char* smem) {
;     ...
;     for (int kt = 0; kt < nk; ++kt) {
;       __syncthreads();
;       GEMM_STORE(ra0, ra1, ra2, ra3, rb0, rb1, rb2, rb3, 0)
;       __syncthreads();
;       {
;         bf16x8 af0[4], bf0[4], af1[4], bf1[4];
;         __builtin_amdgcn_s_setprio(1);
; #pragma unroll
;         for (int i = 0; i < 4; ++i) af0[i] = *(const bf16x8*)(sA + (wm * 64 + i * 16 + l15) * LSTR + quad * 8);
; #pragma unroll
;         for (int j = 0; j < 4; ++j) bf0[j] = *(const bf16x8*)(sB + (wn * 64 + j * 16 + l15) * LSTR + quad * 8);
; #pragma unroll
;         for (int i = 0; i < 4; ++i) af1[i] = *(const bf16x8*)(sA + (wm * 64 + i * 16 + l15) * LSTR + 32 + quad * 8);
; #pragma unroll
;         for (int j = 0; j < 4; ++j) bf1[j] = *(const bf16x8*)(sB + (wn * 64 + j * 16 + l15) * LSTR + 32 + quad * 8);
;         __builtin_amdgcn_sched_barrier(0);
;         if (kt + 1 < nk) GEMM_LOAD(ra0, ra1, ra2, ra3, rb0, rb1, rb2, rb3, (kt + 1) * 64)
.LBB0_1618:
	s_barrier
	s_waitcnt vmcnt(0)
	ds_write_b128 v168, v[64:67]
	ds_write_b128 v168, v[72:75] offset:5120
	ds_write_b128 v168, v[80:83] offset:10240
	ds_write_b128 v168, v[88:91] offset:15360
	ds_write_b128 v168, v[68:71] offset:20480
	ds_write_b128 v168, v[76:79] offset:25600
	ds_write_b128 v168, v[84:87] offset:30720
	ds_write_b128 v168, v[92:95] offset:35840
	v_add_u32_e32 v96, v170, v172
	s_waitcnt lgkmcnt(0)
	s_barrier
	s_setprio 1
	ds_read_b128 v[156:159], v96
	ds_read_b128 v[152:155], v96 offset:2560
	ds_read_b128 v[132:135], v96 offset:5120
	ds_read_b128 v[124:127], v96 offset:7680
	ds_read_b128 v[136:139], v174 offset:20480
	ds_read_b128 v[140:143], v174 offset:23040
	ds_read_b128 v[144:147], v174 offset:25600
	ds_read_b128 v[148:151], v174 offset:28160
	ds_read_b128 v[128:131], v175 offset:64
	ds_read_b128 v[120:123], v175 offset:2624
	ds_read_b128 v[100:103], v175 offset:5184
	ds_read_b128 v[96:99], v175 offset:7744
	ds_read_b128 v[104:107], v176 offset:20544
	ds_read_b128 v[108:111], v176 offset:23104
	ds_read_b128 v[112:115], v176 offset:25664
	ds_read_b128 v[116:119], v176 offset:28224
	s_cmp_gt_u32 s15, 42
	s_cbranch_scc1 .LBB0_1617
	v_lshl_add_u64 v[68:69], v[164:165], 0, s[0:1]
	v_add_co_u32_e32 v64, vcc, 0x5e00000, v68
	v_lshl_add_u64 v[84:85], v[166:167], 0, s[0:1]
	s_nop 0
	v_addc_co_u32_e32 v65, vcc, 0, v69, vcc
	v_add_co_u32_e32 v70, vcc, 0x5e2c000, v68
	s_nop 1
	v_addc_co_u32_e32 v71, vcc, 0, v69, vcc
	global_load_dwordx4 v[64:67], v[64:65], off offset:128
	s_nop 0
	global_load_dwordx4 v[72:75], v[70:71], off offset:128
	v_add_co_u32_e32 v70, vcc, 0x5e58000, v68
	s_nop 1
	v_addc_co_u32_e32 v71, vcc, 0, v69, vcc
	v_add_co_u32_e32 v68, vcc, 0x5e84000, v68
	s_nop 1
	v_addc_co_u32_e32 v69, vcc, 0, v69, vcc
	global_load_dwordx4 v[80:83], v[70:71], off offset:128
	global_load_dwordx4 v[88:91], v[68:69], off offset:128
	v_add_co_u32_e32 v68, vcc, 0x1380000, v84
	s_nop 1
	v_addc_co_u32_e32 v69, vcc, 0, v85, vcc
	v_add_co_u32_e32 v76, vcc, 0x13ac000, v84
	s_nop 1
	v_addc_co_u32_e32 v77, vcc, 0, v85, vcc
	v_add_co_u32_e32 v86, vcc, 0x13d8000, v84
	global_load_dwordx4 v[68:71], v[68:69], off offset:128
	s_nop 0
	global_load_dwordx4 v[76:79], v[76:77], off offset:128
	v_addc_co_u32_e32 v87, vcc, 0, v85, vcc
	v_add_co_u32_e32 v92, vcc, 0x1404000, v84
	s_nop 1
	v_addc_co_u32_e32 v93, vcc, 0, v85, vcc
	global_load_dwordx4 v[84:87], v[86:87], off offset:128
	s_nop 0
	global_load_dwordx4 v[92:95], v[92:93], off offset:128
	s_branch .LBB0_1617
